# v62 + the remaining 12 packed softmax row-sum adds (4th unrolled copy of the MLA chunk loop) split into scalar pairs
# baseline (speedup 1.0000x reference)
.LBB0_657:
	v_fma_f32 v0, v106, s46, -v165
	v_exp_f32_e32 v106, v0
	v_fma_f32 v0, v107, s46, -v165
	v_exp_f32_e32 v130, v0
	v_fma_f32 v0, v108, s46, -v165
	v_exp_f32_e32 v107, v0
	v_fma_f32 v0, v109, s46, -v165
	v_exp_f32_e32 v131, v0
	v_fma_f32 v0, v110, s46, -v165
	v_exp_f32_e32 v108, v0
	v_fma_f32 v0, v111, s46, -v165
	v_exp_f32_e32 v110, v0
	v_fma_f32 v0, v112, s46, -v165
	v_exp_f32_e32 v109, v0
	v_fma_f32 v0, v113, s46, -v165
	v_exp_f32_e32 v111, v0
	v_add_f32_e32 v112, v106, v130
	v_add_f32_e32 v113, v107, v131
	v_cvt_pk_bf16_f32 v106, v106, v130
	v_cvt_pk_bf16_f32 v107, v107, v131
	s_nop 0
	v_add_f32_e32 v0, v112, v113
	v_add_f32_e32 v112, v108, v110
	v_add_f32_e32 v113, v109, v111
	v_add_f32_e32 v133, 0, v0
	v_add_f32_e32 v134, v112, v112
	v_add_f32_e32 v135, v112, v113
	v_fma_f32 v112, v115, s46, -v165
	v_exp_f32_e32 v136, v112
	v_fma_f32 v112, v116, s46, -v165
	v_fma_f32 v113, v119, s46, -v165
	v_fma_f32 v0, v114, s46, -v165
	v_exp_f32_e32 v137, v112
	v_fma_f32 v112, v117, s46, -v165
	v_exp_f32_e32 v114, v113
	v_fma_f32 v113, v120, s46, -v165
	v_exp_f32_e32 v0, v0
	v_exp_f32_e32 v164, v112
	v_fma_f32 v112, v118, s46, -v165
	v_exp_f32_e32 v134, v113
	v_fma_f32 v113, v121, s46, -v165
	v_exp_f32_e32 v112, v112
	v_exp_f32_e32 v132, v113
	v_add_f32_e32 v113, v0, v136
	v_add_f32_e32 v115, v137, v164
	v_add_f32_e32 v116, v112, v114
	v_add_f32_e32 v117, v113, v115
	v_add_f32_e32 v118, v134, v132
	v_add_f32_e32 v119, v135, v133
	v_cvt_pk_bf16_f32 v108, v108, v110
	v_cvt_pk_bf16_f32 v109, v109, v111
	v_cvt_pk_bf16_f32 v110, v0, v136
	v_cvt_pk_bf16_f32 v111, v137, v164
	v_cvt_pk_bf16_f32 v112, v112, v114
	s_nop 0
	v_add_f32_e32 v116, v116, v118
	v_add_f32_e32 v117, v117, v119
	s_nop 0
	v_add_f32_e32 v113, v116, v117
	ds_bpermute_b32 v115, v155, v113
	s_waitcnt lgkmcnt(0)
	v_add_f32_e32 v113, v113, v115
	ds_bpermute_b32 v115, v176, v113
	s_waitcnt lgkmcnt(0)
	v_add_f32_e32 v113, v113, v115
	v_add_f32_e32 v161, v161, v113
	v_cvt_pk_bf16_f32 v113, v134, v132
	ds_read_b64_tr_b16 v[116:117], v175 offset:18560
	ds_read_b64_tr_b16 v[114:115], v175 offset:17408
	ds_read_b64_tr_b16 v[118:119], v175 offset:17440
	ds_read_b64_tr_b16 v[120:121], v175 offset:18592
	s_waitcnt lgkmcnt(2)
	v_mfma_f32_16x16x32_bf16 v[86:89], v[114:117], v[126:129], v[86:89]
	v_mfma_f32_16x16x32_bf16 v[114:117], v[114:117], v[106:109], v[102:105]
	s_waitcnt lgkmcnt(0)
	v_mfma_f32_16x16x32_bf16 v[82:85], v[118:121], v[126:129], v[82:85]
	v_mfma_f32_16x16x32_bf16 v[118:121], v[118:121], v[106:109], v[98:101]
	s_nop 2
	ds_read_b64_tr_b16 v[98:99], v175 offset:17472
	ds_read_b64_tr_b16 v[100:101], v175 offset:18624
	s_waitcnt lgkmcnt(0)
	v_mfma_f32_16x16x32_bf16 v[130:133], v[98:101], v[106:109], v[94:97]
	s_nop 2
	ds_read_b64_tr_b16 v[94:95], v175 offset:17504
	ds_read_b64_tr_b16 v[96:97], v175 offset:18656
	v_mfma_f32_16x16x32_bf16 v[78:81], v[98:101], v[126:129], v[78:81]
	s_waitcnt lgkmcnt(0)
	v_mfma_f32_16x16x32_bf16 v[74:77], v[94:97], v[126:129], v[74:77]
	v_mfma_f32_16x16x32_bf16 v[106:109], v[94:97], v[106:109], v[90:93]
	s_nop 2
	ds_read_b64_tr_b16 v[92:93], v175 offset:27776
	ds_read_b64_tr_b16 v[90:91], v175 offset:26624
	ds_read_b64_tr_b16 v[94:95], v175 offset:26656
	ds_read_b64_tr_b16 v[96:97], v175 offset:27808
	s_add_i32 s44, s44, 4
	s_cmp_ge_u32 s45, s54
	s_waitcnt lgkmcnt(2)
	v_mfma_f32_16x16x32_bf16 v[102:105], v[90:93], v[122:125], v[86:89]
	v_mfma_f32_16x16x32_bf16 v[86:89], v[90:93], v[110:113], v[114:117]
	ds_read_b64_tr_b16 v[90:91], v175 offset:26688
	ds_read_b64_tr_b16 v[92:93], v175 offset:27840
	s_nop 0
	ds_read_b64_tr_b16 v[114:115], v175 offset:26720
	ds_read_b64_tr_b16 v[116:117], v175 offset:27872
	s_waitcnt lgkmcnt(4)
	v_mfma_f32_16x16x32_bf16 v[98:101], v[94:97], v[122:125], v[82:85]
	v_mfma_f32_16x16x32_bf16 v[82:85], v[94:97], v[110:113], v[118:121]
	s_waitcnt lgkmcnt(2)
	v_mfma_f32_16x16x32_bf16 v[94:97], v[90:93], v[122:125], v[78:81]
	v_mfma_f32_16x16x32_bf16 v[78:81], v[90:93], v[110:113], v[130:133]
	s_waitcnt lgkmcnt(0)
	v_mfma_f32_16x16x32_bf16 v[90:93], v[114:117], v[122:125], v[74:77]
	v_mfma_f32_16x16x32_bf16 v[74:77], v[114:117], v[110:113], v[106:109]
	s_cbranch_scc1 .LBB0_634

.LBB0_676:
	v_fma_f32 v0, v122, s46, -v168
	v_exp_f32_e32 v122, v0
	v_fma_f32 v0, v123, s46, -v168
	v_exp_f32_e32 v192, v0
	v_fma_f32 v0, v124, s46, -v168
	v_exp_f32_e32 v123, v0
	v_fma_f32 v0, v125, s46, -v168
	v_exp_f32_e32 v193, v0
	v_fma_f32 v0, v126, s46, -v168
	v_exp_f32_e32 v124, v0
	v_fma_f32 v0, v127, s46, -v168
	v_exp_f32_e32 v194, v0
	v_fma_f32 v0, v128, s46, -v168
	v_exp_f32_e32 v125, v0
	v_fma_f32 v0, v129, s46, -v168
	v_exp_f32_e32 v195, v0
	v_add_f32_e32 v126, v122, v192
	v_add_f32_e32 v127, v123, v193
	s_nop 0
	v_add_f32_e32 v0, v126, v127
	v_add_f32_e32 v126, v124, v194
	v_add_f32_e32 v127, v125, v195
	v_add_f32_e32 v169, 0, v0
	v_add_f32_e32 v196, v126, v126
	v_add_f32_e32 v197, v126, v127
	v_fma_f32 v126, v131, s46, -v168
	v_exp_f32_e32 v164, v126
	v_fma_f32 v126, v132, s46, -v168
	v_exp_f32_e32 v177, v126
	v_fma_f32 v126, v133, s46, -v168
	v_exp_f32_e32 v179, v126
	v_fma_f32 v126, v134, s46, -v168
	v_fma_f32 v0, v130, s46, -v168
	v_exp_f32_e32 v130, v126
	v_fma_f32 v126, v135, s46, -v168
	v_exp_f32_e32 v132, v126
	v_fma_f32 v126, v136, s46, -v168
	v_exp_f32_e32 v0, v0
	v_exp_f32_e32 v196, v126
	v_fma_f32 v126, v137, s46, -v168
	v_exp_f32_e32 v168, v126
	v_add_f32_e32 v131, v0, v164
	v_add_f32_e32 v133, v177, v179
	v_add_f32_e32 v126, v130, v132
	v_add_f32_e32 v127, v131, v133
	v_add_f32_e32 v128, v196, v168
	v_add_f32_e32 v129, v197, v169
	s_nop 0
	v_add_f32_e32 v126, v126, v128
	v_add_f32_e32 v127, v127, v129
	s_nop 0
	v_add_f32_e32 v126, v126, v127
	ds_bpermute_b32 v127, v155, v126
	s_nop 0
	s_waitcnt lgkmcnt(0)
	v_add_f32_e32 v126, v126, v127
	ds_bpermute_b32 v127, v176, v126
	s_waitcnt lgkmcnt(0)
	v_add_f32_e32 v126, v126, v127
	v_add_f32_e32 v160, v160, v126
	s_nop 1
	v_max_f32_e32 v126, v108, v109
	s_nop 0
	v_max_f32_e32 v127, v112, v113
	v_max3_f32 v126, v106, v107, v126
	v_max3_f32 v127, v110, v111, v127
	v_max3_f32 v126, v126, s51, v127
	s_nop 1
	v_max_f32_e32 v127, v116, v117
	s_nop 0
	v_max_f32_e32 v128, v120, v121
	v_max3_f32 v127, v114, v115, v127
	v_max3_f32 v128, v118, v119, v128
	v_max3_f32 v131, v126, v127, v128
	ds_bpermute_b32 v133, v155, v131
	v_cvt_pk_bf16_f32 v126, v122, v192
	v_cvt_pk_bf16_f32 v127, v123, v193
	v_cvt_pk_bf16_f32 v128, v124, v194
	v_cvt_pk_bf16_f32 v129, v125, v195
	s_waitcnt lgkmcnt(0)
	s_nop 0
	v_max_f32_e32 v131, v131, v133
	ds_bpermute_b32 v133, v176, v131
	v_cvt_pk_bf16_f32 v122, v0, v164
	v_cvt_pk_bf16_f32 v123, v177, v179
	v_cvt_pk_bf16_f32 v124, v130, v132
	v_add_f32_e32 v130, 0x41000000, v165
	s_waitcnt lgkmcnt(0)
	s_nop 0
	v_max_f32_e32 v0, v131, v133
	v_mul_f32_e32 v0, 0x3e16c740, v0
	v_cmp_gt_f32_e32 vcc, v0, v130
	v_cvt_pk_bf16_f32 v125, v196, v168
	s_cbranch_vccz .LBB0_657
	s_nop 0
	v_cndmask_b32_e32 v167, v165, v0, vcc
	v_sub_f32_e32 v0, v165, v167
	v_exp_f32_e32 v0, v0
	v_mov_b32_e32 v165, v167
	v_mul_f32_e32 v161, v161, v0
	v_pk_mul_f32 v[104:105], v[104:105], v[0:1] op_sel_hi:[1,0]
	v_pk_mul_f32 v[102:103], v[102:103], v[0:1] op_sel_hi:[1,0]
	v_pk_mul_f32 v[100:101], v[100:101], v[0:1] op_sel_hi:[1,0]
	v_pk_mul_f32 v[98:99], v[98:99], v[0:1] op_sel_hi:[1,0]
	v_pk_mul_f32 v[96:97], v[96:97], v[0:1] op_sel_hi:[1,0]
	v_pk_mul_f32 v[94:95], v[94:95], v[0:1] op_sel_hi:[1,0]
	v_pk_mul_f32 v[92:93], v[92:93], v[0:1] op_sel_hi:[1,0]
	v_pk_mul_f32 v[90:91], v[90:91], v[0:1] op_sel_hi:[1,0]
	s_branch .LBB0_657
